# grid barrier: acquire-side buffer_inv sc1 issued right after the arrival atomic (overlaps the wait; no L1-allocating loads until release is observed), post-poll wait kept (stacked on v17 + diff loop h
# speedup vs baseline: 1.0100x; 1.0100x over previous
; DI int mk_tid(int wv) { int w = wv; asm volatile("" : "+s"(w)); int l = __builtin_amdgcn_mbcnt_hi(~0u, __builtin_amdgcn_mbcnt_lo(~0u, 0u)); asm volatile("" : "+v"(l)); return w * 64 + l; }
; DI unsigned xcc_id() { return (unsigned)__builtin_amdgcn_s_getreg((3 << 11) | 20) & 0xFu; }
; DI void grid_barrier(int wv, unsigned* bar_, unsigned k, LAS unsigned* stash) {
;     ...
;     if (mk_tid(wv) == 0) {
;         const unsigned xcc = xcc_id(), nx = stash[0], nxcc = stash[1];
;         const unsigned old = __hip_atomic_fetch_add(bar + 64 * (17 + xcc), 1u, __ATOMIC_RELAXED, __HIP_MEMORY_SCOPE_AGENT);
;         if (old == k * nx - 1u) {
;             __builtin_amdgcn_fence(__ATOMIC_RELEASE, "agent");
;             asm volatile("s_waitcnt vmcnt(0)" ::: "memory");
;             const unsigned old2 = __hip_atomic_fetch_add(bar + 64 * 33, 1u, __ATOMIC_RELAXED, __HIP_MEMORY_SCOPE_AGENT);
;             if (old2 == k * nxcc - 1u) __hip_atomic_store(bar + 64 * 34, k, __ATOMIC_RELAXED, __HIP_MEMORY_SCOPE_AGENT);
;         }
.LBB0_108:
	s_or_b64 exec, exec, s[8:9]
	s_waitcnt vmcnt(0)
	buffer_inv sc1
	v_readfirstlane_b32 s2, v5
	s_nop 1
	v_add_u32_e32 v6, s2, v4
	s_waitcnt lgkmcnt(0)
	v_mad_u64_u32 v[4:5], s[6:7], v2, v0, -1
	v_cmp_eq_u32_e32 vcc, v6, v4
	s_and_saveexec_b64 s[6:7], vcc
	s_cbranch_execz .LBB0_113
	s_mov_b64 s[8:9], exec
	buffer_wbl2 sc1
	s_waitcnt vmcnt(0)
	v_mbcnt_lo_u32_b32 v2, s8, 0
	v_mbcnt_hi_u32_b32 v2, s9, v2
	v_cmp_eq_u32_e32 vcc, 0, v2
	s_and_saveexec_b64 s[10:11], vcc
	s_cbranch_execz .LBB0_111
	s_bcnt1_i32_b64 s2, s[8:9]
	v_mov_b32_e32 v4, s2
	global_atomic_add v4, v240, v4, s[4:5] offset:256 sc0

; DI void grid_barrier(int wv, unsigned* bar_, unsigned k, LAS unsigned* stash) {
;     ...
;         while (__hip_atomic_load(bar + 64 * 34, __ATOMIC_RELAXED, __HIP_MEMORY_SCOPE_AGENT) < k) __builtin_amdgcn_s_sleep(2);
;         __builtin_amdgcn_fence(__ATOMIC_ACQUIRE, "agent");
;         asm volatile("s_waitcnt vmcnt(0)" ::: "memory");
.LBB0_116:
	s_or_b64 exec, exec, s[6:7]
	s_nop 0
	s_waitcnt vmcnt(0)

; DI int mk_tid(int wv) { int w = wv; asm volatile("" : "+s"(w)); int l = __builtin_amdgcn_mbcnt_hi(~0u, __builtin_amdgcn_mbcnt_lo(~0u, 0u)); asm volatile("" : "+v"(l)); return w * 64 + l; }
; DI unsigned xcc_id() { return (unsigned)__builtin_amdgcn_s_getreg((3 << 11) | 20) & 0xFu; }
; DI void grid_barrier(int wv, unsigned* bar_, unsigned k, LAS unsigned* stash) {
;     ...
;     if (mk_tid(wv) == 0) {
;         const unsigned xcc = xcc_id(), nx = stash[0], nxcc = stash[1];
;         const unsigned old = __hip_atomic_fetch_add(bar + 64 * (17 + xcc), 1u, __ATOMIC_RELAXED, __HIP_MEMORY_SCOPE_AGENT);
;         if (old == k * nx - 1u) {
;             __builtin_amdgcn_fence(__ATOMIC_RELEASE, "agent");
;             asm volatile("s_waitcnt vmcnt(0)" ::: "memory");
;             const unsigned old2 = __hip_atomic_fetch_add(bar + 64 * 33, 1u, __ATOMIC_RELAXED, __HIP_MEMORY_SCOPE_AGENT);
;             if (old2 == k * nxcc - 1u) __hip_atomic_store(bar + 64 * 34, k, __ATOMIC_RELAXED, __HIP_MEMORY_SCOPE_AGENT);
;         }
.LBB0_158:
	s_or_b64 exec, exec, s[8:9]
	s_waitcnt vmcnt(0)
	buffer_inv sc1
	v_readfirstlane_b32 s2, v4
	s_waitcnt lgkmcnt(0)
	v_mad_u64_u32 v[4:5], s[6:7], v2, v167, -1
	v_add_u32_e32 v0, s2, v0
	v_cmp_eq_u32_e32 vcc, v0, v4
	s_and_saveexec_b64 s[6:7], vcc
	s_cbranch_execz .LBB0_163
	s_mov_b64 s[8:9], exec
	buffer_wbl2 sc1
	s_waitcnt vmcnt(0)
	v_mbcnt_lo_u32_b32 v0, s8, 0
	v_mbcnt_hi_u32_b32 v0, s9, v0
	v_cmp_eq_u32_e32 vcc, 0, v0
	s_and_saveexec_b64 s[10:11], vcc
	s_cbranch_execz .LBB0_161
	s_bcnt1_i32_b64 s2, s[8:9]
	v_mov_b32_e32 v2, s2
	global_atomic_add v2, v240, v2, s[4:5] offset:256 sc0

; DI int mk_tid(int wv) { int w = wv; asm volatile("" : "+s"(w)); int l = __builtin_amdgcn_mbcnt_hi(~0u, __builtin_amdgcn_mbcnt_lo(~0u, 0u)); asm volatile("" : "+v"(l)); return w * 64 + l; }
; DI unsigned xcc_id() { return (unsigned)__builtin_amdgcn_s_getreg((3 << 11) | 20) & 0xFu; }
; DI void grid_barrier(int wv, unsigned* bar_, unsigned k, LAS unsigned* stash) {
;     ...
;     if (mk_tid(wv) == 0) {
;         const unsigned xcc = xcc_id(), nx = stash[0], nxcc = stash[1];
;         const unsigned old = __hip_atomic_fetch_add(bar + 64 * (17 + xcc), 1u, __ATOMIC_RELAXED, __HIP_MEMORY_SCOPE_AGENT);
;         if (old == k * nx - 1u) {
;             __builtin_amdgcn_fence(__ATOMIC_RELEASE, "agent");
;             asm volatile("s_waitcnt vmcnt(0)" ::: "memory");
;             const unsigned old2 = __hip_atomic_fetch_add(bar + 64 * 33, 1u, __ATOMIC_RELAXED, __HIP_MEMORY_SCOPE_AGENT);
;             if (old2 == k * nxcc - 1u) __hip_atomic_store(bar + 64 * 34, k, __ATOMIC_RELAXED, __HIP_MEMORY_SCOPE_AGENT);
;         }
.LBB0_500:
	s_or_b64 exec, exec, s[22:23]
	s_waitcnt vmcnt(0)
	buffer_inv sc1
	v_readfirstlane_b32 s2, v5
	s_nop 1
	v_add_u32_e32 v6, s2, v4
	s_waitcnt lgkmcnt(0)
	v_mad_u64_u32 v[4:5], s[8:9], v2, v0, -1
	v_cmp_eq_u32_e32 vcc, v6, v4
	s_and_saveexec_b64 s[8:9], vcc
	s_cbranch_execz .LBB0_505
	s_mov_b64 s[22:23], exec
	buffer_wbl2 sc1
	s_waitcnt vmcnt(0)
	v_mbcnt_lo_u32_b32 v2, s22, 0
	v_mbcnt_hi_u32_b32 v2, s23, v2
	v_cmp_eq_u32_e32 vcc, 0, v2
	s_and_saveexec_b64 s[24:25], vcc
	s_cbranch_execz .LBB0_503
	s_bcnt1_i32_b64 s2, s[22:23]
	v_mov_b32_e32 v4, s2
	global_atomic_add v4, v240, v4, s[6:7] offset:256 sc0

; DI void grid_barrier(int wv, unsigned* bar_, unsigned k, LAS unsigned* stash) {
;     ...
;         while (__hip_atomic_load(bar + 64 * 34, __ATOMIC_RELAXED, __HIP_MEMORY_SCOPE_AGENT) < k) __builtin_amdgcn_s_sleep(2);
;         __builtin_amdgcn_fence(__ATOMIC_ACQUIRE, "agent");
;         asm volatile("s_waitcnt vmcnt(0)" ::: "memory");
.LBB0_508:
	s_or_b64 exec, exec, s[8:9]
	s_nop 0
	s_waitcnt vmcnt(0)

; DI int mk_tid(int wv) { int w = wv; asm volatile("" : "+s"(w)); int l = __builtin_amdgcn_mbcnt_hi(~0u, __builtin_amdgcn_mbcnt_lo(~0u, 0u)); asm volatile("" : "+v"(l)); return w * 64 + l; }
; DI unsigned xcc_id() { return (unsigned)__builtin_amdgcn_s_getreg((3 << 11) | 20) & 0xFu; }
; DI void grid_barrier(int wv, unsigned* bar_, unsigned k, LAS unsigned* stash) {
;     ...
;     if (mk_tid(wv) == 0) {
;         const unsigned xcc = xcc_id(), nx = stash[0], nxcc = stash[1];
;         const unsigned old = __hip_atomic_fetch_add(bar + 64 * (17 + xcc), 1u, __ATOMIC_RELAXED, __HIP_MEMORY_SCOPE_AGENT);
;         if (old == k * nx - 1u) {
;             __builtin_amdgcn_fence(__ATOMIC_RELEASE, "agent");
;             asm volatile("s_waitcnt vmcnt(0)" ::: "memory");
;             const unsigned old2 = __hip_atomic_fetch_add(bar + 64 * 33, 1u, __ATOMIC_RELAXED, __HIP_MEMORY_SCOPE_AGENT);
;             if (old2 == k * nxcc - 1u) __hip_atomic_store(bar + 64 * 34, k, __ATOMIC_RELAXED, __HIP_MEMORY_SCOPE_AGENT);
;         }
.LBB0_629:
	s_or_b64 exec, exec, s[8:9]
	s_waitcnt vmcnt(0)
	buffer_inv sc1
	v_readfirstlane_b32 s2, v5
	s_nop 1
	v_add_u32_e32 v6, s2, v4
	s_waitcnt lgkmcnt(0)
	v_mad_u64_u32 v[4:5], s[6:7], v2, v0, -1
	v_cmp_eq_u32_e32 vcc, v6, v4
	s_and_saveexec_b64 s[6:7], vcc
	s_cbranch_execz .LBB0_634
	s_mov_b64 s[8:9], exec
	buffer_wbl2 sc1
	s_waitcnt vmcnt(0)
	v_mbcnt_lo_u32_b32 v2, s8, 0
	v_mbcnt_hi_u32_b32 v2, s9, v2
	v_cmp_eq_u32_e32 vcc, 0, v2
	s_and_saveexec_b64 s[20:21], vcc
	s_cbranch_execz .LBB0_632
	s_bcnt1_i32_b64 s2, s[8:9]
	v_mov_b32_e32 v4, s2
	global_atomic_add v4, v240, v4, s[4:5] offset:256 sc0
